# main G1 K-loop: loop-carried pointer and counter SALU hoisted from the post-barrier load segment into the preceding MFMA segment
# baseline (speedup 1.0000x reference)
.LBB0_56:
	s_ashr_i32 s95, s94, 31
	s_lshl_b64 s[6:7], s[94:95], 19
	v_readlane_b32 s9, v253, 5
	s_add_u32 s80, s9, s6
	v_readlane_b32 s6, v253, 6
	s_addc_u32 s81, s6, s7
	s_and_b64 s[6:7], s[42:43], exec
	s_cselect_b32 s9, s81, s1
	s_cselect_b32 s11, s80, s0
	s_ashr_i32 s93, s92, 31
	s_lshl_b64 s[6:7], s[92:93], 19
	v_readlane_b32 s12, v253, 61
	s_add_u32 s82, s12, s6
	v_readlane_b32 s6, v253, 62
	s_addc_u32 s83, s6, s7
	s_and_b64 s[6:7], s[42:43], exec
	s_cselect_b32 s12, s83, s5
	s_cselect_b32 s13, s82, s4
	s_add_u32 s0, s0, 0x40080
	s_addc_u32 s1, s1, 0
	s_add_u32 s14, s4, 0x100
	v_mov_b32_e32 v2, 0
	s_addc_u32 s15, s5, 0
	s_mov_b32 s16, -2
	v_mov_b32_e32 v3, v2
	v_mov_b32_e32 v4, v2
	v_mov_b32_e32 v5, v2
	v_mov_b32_e32 v6, v2
	v_mov_b32_e32 v7, v2
	v_mov_b32_e32 v8, v2
	v_mov_b32_e32 v9, v2
	v_mov_b32_e32 v26, v2
	v_mov_b32_e32 v27, v2
	v_mov_b32_e32 v28, v2
	v_mov_b32_e32 v29, v2
	v_mov_b32_e32 v30, v2
	v_mov_b32_e32 v31, v2
	v_mov_b32_e32 v32, v2
	v_mov_b32_e32 v33, v2
	v_mov_b32_e32 v50, v2
	v_mov_b32_e32 v51, v2
	v_mov_b32_e32 v52, v2
	v_mov_b32_e32 v53, v2
	v_mov_b32_e32 v54, v2
	v_mov_b32_e32 v55, v2
	v_mov_b32_e32 v56, v2
	v_mov_b32_e32 v57, v2
	v_mov_b32_e32 v66, v2
	v_mov_b32_e32 v67, v2
	v_mov_b32_e32 v68, v2
	v_mov_b32_e32 v69, v2
	v_mov_b32_e32 v70, v2
	v_mov_b32_e32 v71, v2
	v_mov_b32_e32 v72, v2
	v_mov_b32_e32 v73, v2
	v_mov_b32_e32 v10, v2
	v_mov_b32_e32 v11, v2
	v_mov_b32_e32 v12, v2
	v_mov_b32_e32 v13, v2
	v_mov_b32_e32 v14, v2
	v_mov_b32_e32 v15, v2
	v_mov_b32_e32 v16, v2
	v_mov_b32_e32 v17, v2
	v_mov_b32_e32 v42, v2
	v_mov_b32_e32 v43, v2
	v_mov_b32_e32 v44, v2
	v_mov_b32_e32 v45, v2
	v_mov_b32_e32 v46, v2
	v_mov_b32_e32 v47, v2
	v_mov_b32_e32 v48, v2
	v_mov_b32_e32 v49, v2
	v_mov_b32_e32 v58, v2
	v_mov_b32_e32 v59, v2
	v_mov_b32_e32 v60, v2
	v_mov_b32_e32 v61, v2
	v_mov_b32_e32 v62, v2
	v_mov_b32_e32 v63, v2
	v_mov_b32_e32 v64, v2
	v_mov_b32_e32 v65, v2
	v_mov_b32_e32 v74, v2
	v_mov_b32_e32 v75, v2
	v_mov_b32_e32 v76, v2
	v_mov_b32_e32 v77, v2
	v_mov_b32_e32 v78, v2
	v_mov_b32_e32 v79, v2
	v_mov_b32_e32 v80, v2
	v_mov_b32_e32 v81, v2
	v_mov_b32_e32 v82, v2
	v_mov_b32_e32 v83, v2
	v_mov_b32_e32 v84, v2
	v_mov_b32_e32 v85, v2
	v_mov_b32_e32 v86, v2
	v_mov_b32_e32 v87, v2
	v_mov_b32_e32 v88, v2
	v_mov_b32_e32 v89, v2
	v_mov_b32_e32 v98, v2
	v_mov_b32_e32 v99, v2
	v_mov_b32_e32 v100, v2
	v_mov_b32_e32 v101, v2
	v_mov_b32_e32 v102, v2
	v_mov_b32_e32 v103, v2
	v_mov_b32_e32 v104, v2
	v_mov_b32_e32 v105, v2
	v_mov_b32_e32 v114, v2
	v_mov_b32_e32 v115, v2
	v_mov_b32_e32 v116, v2
	v_mov_b32_e32 v117, v2
	v_mov_b32_e32 v118, v2
	v_mov_b32_e32 v119, v2
	v_mov_b32_e32 v120, v2
	v_mov_b32_e32 v121, v2
	v_mov_b32_e32 v130, v2
	v_mov_b32_e32 v131, v2
	v_mov_b32_e32 v132, v2
	v_mov_b32_e32 v133, v2
	v_mov_b32_e32 v134, v2
	v_mov_b32_e32 v135, v2
	v_mov_b32_e32 v136, v2
	v_mov_b32_e32 v137, v2
	v_mov_b32_e32 v90, v2
	v_mov_b32_e32 v91, v2
	v_mov_b32_e32 v92, v2
	v_mov_b32_e32 v93, v2
	v_mov_b32_e32 v94, v2
	v_mov_b32_e32 v95, v2
	v_mov_b32_e32 v96, v2
	v_mov_b32_e32 v97, v2
	v_mov_b32_e32 v106, v2
	v_mov_b32_e32 v107, v2
	v_mov_b32_e32 v108, v2
	v_mov_b32_e32 v109, v2
	v_mov_b32_e32 v110, v2
	v_mov_b32_e32 v111, v2
	v_mov_b32_e32 v112, v2
	v_mov_b32_e32 v113, v2
	v_mov_b32_e32 v122, v2
	v_mov_b32_e32 v123, v2
	v_mov_b32_e32 v124, v2
	v_mov_b32_e32 v125, v2
	v_mov_b32_e32 v126, v2
	v_mov_b32_e32 v127, v2
	v_mov_b32_e32 v128, v2
	v_mov_b32_e32 v129, v2
	v_mov_b32_e32 v138, v2
	v_mov_b32_e32 v139, v2
	v_mov_b32_e32 v140, v2
	v_mov_b32_e32 v141, v2
	v_mov_b32_e32 v142, v2
	v_mov_b32_e32 v143, v2
	v_mov_b32_e32 v144, v2
	v_mov_b32_e32 v145, v2
	s_waitcnt vmcnt(0)
	s_add_u32 s4, s0, 0xfffc0080
	s_addc_u32 s5, s1, -1
	s_add_i32 s17, 0, 0x10000
	s_cmp_eq_u32 s16, 12
	s_cselect_b32 s7, s9, s5
	s_cselect_b32 s6, s11, s4
	v_add_u32_e32 v0, s17, v198
	s_cselect_b32 s5, s12, s15
	s_cselect_b32 s4, s13, s14
	s_add_i32 s20, 0, 0x14000
.LBB0_57:
	ds_read_b128 v[18:21], v0
	ds_read_b128 v[22:25], v0 offset:1024
	ds_read_b128 v[34:37], v0 offset:2048
	ds_read_b128 v[38:41], v0 offset:3072
	v_add_u32_e32 v0, s20, v198
	ds_read_b128 v[146:149], v0
	ds_read_b128 v[150:153], v0 offset:1024
	ds_read_b128 v[172:175], v0 offset:2048
	ds_read_b128 v[176:179], v0 offset:3072
	v_lshl_add_u64 v[188:189], s[0:1], 0, v[168:169]
	s_add_i32 m0, s69, 0xc000
	ds_read_b128 v[180:183], v200
	ds_read_b128 v[184:187], v200 offset:1024
	ds_read_b128 v[202:205], v200 offset:2048
	ds_read_b128 v[206:209], v200 offset:3072
	ds_read_b128 v[210:213], v200 offset:4096
	ds_read_b128 v[214:217], v200 offset:5120
	ds_read_b128 v[218:221], v200 offset:6144
	ds_read_b128 v[234:237], v200 offset:7168
	global_load_lds_dwordx4 v[188:189], off
	v_lshl_add_u64 v[188:189], s[0:1], 0, v[170:171]
	s_add_i32 m0, s69, 0xe000
	s_nop 0
	global_load_lds_dwordx4 v[188:189], off
	s_waitcnt vmcnt(8)
	s_waitcnt lgkmcnt(0)
	s_barrier
	s_setprio 1
	s_waitcnt lgkmcnt(0)
	v_mfma_f32_16x16x32_bf16 v[142:145], v[18:21], v[180:183], v[142:145]
	v_mfma_f32_16x16x32_bf16 v[138:141], v[34:37], v[180:183], v[138:141]
	v_mfma_f32_16x16x32_bf16 v[126:129], v[18:21], v[202:205], v[126:129]
	v_mfma_f32_16x16x32_bf16 v[122:125], v[34:37], v[202:205], v[122:125]
	v_mfma_f32_16x16x32_bf16 v[110:113], v[18:21], v[210:213], v[110:113]
	v_mfma_f32_16x16x32_bf16 v[106:109], v[34:37], v[210:213], v[106:109]
	v_mfma_f32_16x16x32_bf16 v[94:97], v[18:21], v[218:221], v[94:97]
	v_mfma_f32_16x16x32_bf16 v[90:93], v[34:37], v[218:221], v[90:93]
	v_mfma_f32_16x16x32_bf16 v[142:145], v[22:25], v[184:187], v[142:145]
	v_mfma_f32_16x16x32_bf16 v[138:141], v[38:41], v[184:187], v[138:141]
	v_mfma_f32_16x16x32_bf16 v[126:129], v[22:25], v[206:209], v[126:129]
	v_mfma_f32_16x16x32_bf16 v[122:125], v[38:41], v[206:209], v[122:125]
	v_mfma_f32_16x16x32_bf16 v[110:113], v[22:25], v[214:217], v[110:113]
	v_mfma_f32_16x16x32_bf16 v[106:109], v[38:41], v[214:217], v[106:109]
	v_mfma_f32_16x16x32_bf16 v[94:97], v[22:25], v[234:237], v[94:97]
	v_mfma_f32_16x16x32_bf16 v[90:93], v[38:41], v[234:237], v[90:93]
	s_setprio 0
	s_setprio 1
	v_mfma_f32_16x16x32_bf16 v[134:137], v[146:149], v[180:183], v[134:137]
	v_mfma_f32_16x16x32_bf16 v[130:133], v[172:175], v[180:183], v[130:133]
	v_mfma_f32_16x16x32_bf16 v[118:121], v[146:149], v[202:205], v[118:121]
	v_mfma_f32_16x16x32_bf16 v[114:117], v[172:175], v[202:205], v[114:117]
	v_mfma_f32_16x16x32_bf16 v[102:105], v[146:149], v[210:213], v[102:105]
	v_mfma_f32_16x16x32_bf16 v[98:101], v[172:175], v[210:213], v[98:101]
	v_mfma_f32_16x16x32_bf16 v[86:89], v[146:149], v[218:221], v[86:89]
	v_mfma_f32_16x16x32_bf16 v[82:85], v[172:175], v[218:221], v[82:85]
	v_mfma_f32_16x16x32_bf16 v[134:137], v[150:153], v[184:187], v[134:137]
	v_mfma_f32_16x16x32_bf16 v[130:133], v[176:179], v[184:187], v[130:133]
	v_mfma_f32_16x16x32_bf16 v[118:121], v[150:153], v[206:209], v[118:121]
	v_mfma_f32_16x16x32_bf16 v[114:117], v[176:179], v[206:209], v[114:117]
	v_mfma_f32_16x16x32_bf16 v[102:105], v[150:153], v[214:217], v[102:105]
	v_mfma_f32_16x16x32_bf16 v[98:101], v[176:179], v[214:217], v[98:101]
	v_mfma_f32_16x16x32_bf16 v[86:89], v[150:153], v[234:237], v[86:89]
	v_mfma_f32_16x16x32_bf16 v[82:85], v[176:179], v[234:237], v[82:85]
	s_setprio 0
	s_barrier
	s_add_i32 s17, s17, s87
	v_lshl_add_u64 v[188:189], s[4:5], 0, v[158:159]
	s_mov_b32 m0, s17
	ds_read_b128 v[180:183], v200 offset:16384
	ds_read_b128 v[184:187], v200 offset:17408
	ds_read_b128 v[202:205], v200 offset:18432
	ds_read_b128 v[206:209], v200 offset:19456
	ds_read_b128 v[210:213], v200 offset:20480
	ds_read_b128 v[214:217], v200 offset:21504
	ds_read_b128 v[218:221], v200 offset:22528
	ds_read_b128 v[234:237], v200 offset:23552
	global_load_lds_dwordx4 v[188:189], off
	s_add_i32 m0, s17, 0x2000
	s_add_u32 s18, s4, 0x40000
	v_lshl_add_u64 v[222:223], s[4:5], 0, v[154:155]
	s_addc_u32 s19, s5, 0
	s_add_i32 s17, s20, s87
	global_load_lds_dwordx4 v[222:223], off
	v_lshl_add_u64 v[238:239], s[18:19], 0, v[158:159]
	s_mov_b32 m0, s17
	v_lshl_add_u64 v[240:241], s[6:7], 0, v[156:157]
	global_load_lds_dwordx4 v[238:239], off
	v_lshl_add_u64 v[238:239], s[18:19], 0, v[154:155]
	s_add_i32 m0, s17, 0x2000
	s_nop 0
	global_load_lds_dwordx4 v[238:239], off
	v_lshl_add_u64 v[238:239], s[6:7], 0, v[160:161]
	s_mov_b32 m0, s69
	s_nop 0
	global_load_lds_dwordx4 v[238:239], off
	s_mov_b32 m0, s76
	s_nop 0
	global_load_lds_dwordx4 v[240:241], off
	s_waitcnt vmcnt(8)
	s_waitcnt lgkmcnt(0)
	s_barrier
	s_setprio 1
	s_waitcnt lgkmcnt(0)
	v_mfma_f32_16x16x32_bf16 v[78:81], v[18:21], v[180:183], v[78:81]
	v_mfma_f32_16x16x32_bf16 v[74:77], v[34:37], v[180:183], v[74:77]
	v_mfma_f32_16x16x32_bf16 v[62:65], v[18:21], v[202:205], v[62:65]
	v_mfma_f32_16x16x32_bf16 v[58:61], v[34:37], v[202:205], v[58:61]
	v_mfma_f32_16x16x32_bf16 v[46:49], v[18:21], v[210:213], v[46:49]
	v_mfma_f32_16x16x32_bf16 v[42:45], v[34:37], v[210:213], v[42:45]
	v_mfma_f32_16x16x32_bf16 v[14:17], v[18:21], v[218:221], v[14:17]
	v_mfma_f32_16x16x32_bf16 v[10:13], v[34:37], v[218:221], v[10:13]
	v_mfma_f32_16x16x32_bf16 v[78:81], v[22:25], v[184:187], v[78:81]
	v_mfma_f32_16x16x32_bf16 v[74:77], v[38:41], v[184:187], v[74:77]
	v_mfma_f32_16x16x32_bf16 v[62:65], v[22:25], v[206:209], v[62:65]
	v_mfma_f32_16x16x32_bf16 v[58:61], v[38:41], v[206:209], v[58:61]
	v_mfma_f32_16x16x32_bf16 v[46:49], v[22:25], v[214:217], v[46:49]
	v_mfma_f32_16x16x32_bf16 v[42:45], v[38:41], v[214:217], v[42:45]
	v_mfma_f32_16x16x32_bf16 v[14:17], v[22:25], v[234:237], v[14:17]
	v_mfma_f32_16x16x32_bf16 v[10:13], v[38:41], v[234:237], v[10:13]
	s_setprio 0
	s_setprio 1
	v_mfma_f32_16x16x32_bf16 v[30:33], v[146:149], v[210:213], v[30:33]
	v_mfma_f32_16x16x32_bf16 v[26:29], v[172:175], v[210:213], v[26:29]
	v_mfma_f32_16x16x32_bf16 v[6:9], v[146:149], v[218:221], v[6:9]
	v_mfma_f32_16x16x32_bf16 v[2:5], v[172:175], v[218:221], v[2:5]
	v_mfma_f32_16x16x32_bf16 v[18:21], v[146:149], v[180:183], v[70:73]
	v_mfma_f32_16x16x32_bf16 v[22:25], v[172:175], v[180:183], v[66:69]
	v_mfma_f32_16x16x32_bf16 v[34:37], v[146:149], v[202:205], v[54:57]
	v_mfma_f32_16x16x32_bf16 v[38:41], v[172:175], v[202:205], v[50:53]
	v_mfma_f32_16x16x32_bf16 v[30:33], v[150:153], v[214:217], v[30:33]
	v_mfma_f32_16x16x32_bf16 v[26:29], v[176:179], v[214:217], v[26:29]
	v_mfma_f32_16x16x32_bf16 v[6:9], v[150:153], v[234:237], v[6:9]
	v_mfma_f32_16x16x32_bf16 v[2:5], v[176:179], v[234:237], v[2:5]
	v_mfma_f32_16x16x32_bf16 v[18:21], v[150:153], v[184:187], v[18:21]
	v_mfma_f32_16x16x32_bf16 v[22:25], v[176:179], v[184:187], v[22:25]
	v_mfma_f32_16x16x32_bf16 v[34:37], v[150:153], v[206:209], v[34:37]
	v_mfma_f32_16x16x32_bf16 v[38:41], v[176:179], v[206:209], v[38:41]
	s_setprio 0
	s_barrier
	s_add_i32 s17, 0, 0x18000
	v_add_u32_e32 v0, s17, v198
	s_add_i32 s18, 0, 0x1c000
	ds_read_b128 v[50:53], v0
	ds_read_b128 v[54:57], v0 offset:1024
	ds_read_b128 v[66:69], v0 offset:2048
	ds_read_b128 v[70:73], v0 offset:3072
	v_add_u32_e32 v0, s18, v198
	ds_read_b128 v[146:149], v0
	ds_read_b128 v[150:153], v0 offset:1024
	ds_read_b128 v[172:175], v0 offset:2048
	ds_read_b128 v[176:179], v0 offset:3072
	s_add_u32 s6, s6, 0x40000
	s_addc_u32 s7, s7, 0
	s_mov_b32 m0, s77
	v_lshl_add_u64 v[242:243], s[6:7], 0, v[160:161]
	ds_read_b128 v[180:183], v200 offset:32768
	ds_read_b128 v[184:187], v200 offset:33792
	ds_read_b128 v[202:205], v200 offset:34816
	ds_read_b128 v[206:209], v200 offset:35840
	ds_read_b128 v[210:213], v200 offset:36864
	ds_read_b128 v[214:217], v200 offset:37888
	ds_read_b128 v[218:221], v200 offset:38912
	ds_read_b128 v[234:237], v200 offset:39936
	global_load_lds_dwordx4 v[242:243], off
	v_lshl_add_u64 v[242:243], s[6:7], 0, v[156:157]
	s_mov_b32 m0, s96
	s_nop 0
	global_load_lds_dwordx4 v[242:243], off
	s_waitcnt vmcnt(8)
	s_waitcnt lgkmcnt(0)
	s_barrier
	s_setprio 1
	s_waitcnt lgkmcnt(0)
	v_mfma_f32_16x16x32_bf16 v[142:145], v[50:53], v[180:183], v[142:145]
	v_mfma_f32_16x16x32_bf16 v[138:141], v[66:69], v[180:183], v[138:141]
	v_mfma_f32_16x16x32_bf16 v[126:129], v[50:53], v[202:205], v[126:129]
	v_mfma_f32_16x16x32_bf16 v[122:125], v[66:69], v[202:205], v[122:125]
	v_mfma_f32_16x16x32_bf16 v[110:113], v[50:53], v[210:213], v[110:113]
	v_mfma_f32_16x16x32_bf16 v[106:109], v[66:69], v[210:213], v[106:109]
	v_mfma_f32_16x16x32_bf16 v[94:97], v[50:53], v[218:221], v[94:97]
	v_mfma_f32_16x16x32_bf16 v[90:93], v[66:69], v[218:221], v[90:93]
	v_mfma_f32_16x16x32_bf16 v[142:145], v[54:57], v[184:187], v[142:145]
	v_mfma_f32_16x16x32_bf16 v[138:141], v[70:73], v[184:187], v[138:141]
	v_mfma_f32_16x16x32_bf16 v[126:129], v[54:57], v[206:209], v[126:129]
	v_mfma_f32_16x16x32_bf16 v[122:125], v[70:73], v[206:209], v[122:125]
	v_mfma_f32_16x16x32_bf16 v[110:113], v[54:57], v[214:217], v[110:113]
	v_mfma_f32_16x16x32_bf16 v[106:109], v[70:73], v[214:217], v[106:109]
	v_mfma_f32_16x16x32_bf16 v[94:97], v[54:57], v[234:237], v[94:97]
	v_mfma_f32_16x16x32_bf16 v[90:93], v[70:73], v[234:237], v[90:93]
	s_setprio 0
	s_setprio 1
	v_mfma_f32_16x16x32_bf16 v[134:137], v[146:149], v[180:183], v[134:137]
	v_mfma_f32_16x16x32_bf16 v[130:133], v[172:175], v[180:183], v[130:133]
	v_mfma_f32_16x16x32_bf16 v[118:121], v[146:149], v[202:205], v[118:121]
	v_mfma_f32_16x16x32_bf16 v[114:117], v[172:175], v[202:205], v[114:117]
	v_mfma_f32_16x16x32_bf16 v[102:105], v[146:149], v[210:213], v[102:105]
	v_mfma_f32_16x16x32_bf16 v[98:101], v[172:175], v[210:213], v[98:101]
	v_mfma_f32_16x16x32_bf16 v[86:89], v[146:149], v[218:221], v[86:89]
	v_mfma_f32_16x16x32_bf16 v[82:85], v[172:175], v[218:221], v[82:85]
	v_mfma_f32_16x16x32_bf16 v[134:137], v[150:153], v[184:187], v[134:137]
	v_mfma_f32_16x16x32_bf16 v[130:133], v[176:179], v[184:187], v[130:133]
	v_mfma_f32_16x16x32_bf16 v[118:121], v[150:153], v[206:209], v[118:121]
	v_mfma_f32_16x16x32_bf16 v[114:117], v[176:179], v[206:209], v[114:117]
	v_mfma_f32_16x16x32_bf16 v[102:105], v[150:153], v[214:217], v[102:105]
	v_mfma_f32_16x16x32_bf16 v[98:101], v[176:179], v[214:217], v[98:101]
	v_mfma_f32_16x16x32_bf16 v[86:89], v[150:153], v[234:237], v[86:89]
	v_mfma_f32_16x16x32_bf16 v[82:85], v[176:179], v[234:237], v[82:85]
	s_setprio 0
	s_barrier
	s_add_i32 s6, s17, s87
	v_lshl_add_u64 v[188:189], v[188:189], 0, s[48:49]
	s_mov_b32 m0, s6
	ds_read_b128 v[180:183], v200 offset:49152
	ds_read_b128 v[184:187], v200 offset:50176
	ds_read_b128 v[202:205], v200 offset:51200
	ds_read_b128 v[206:209], v200 offset:52224
	ds_read_b128 v[210:213], v200 offset:53248
	ds_read_b128 v[214:217], v200 offset:54272
	ds_read_b128 v[218:221], v200 offset:55296
	ds_read_b128 v[234:237], v200 offset:56320
	global_load_lds_dwordx4 v[188:189], off
	s_add_i32 m0, s6, 0x2000
	s_add_u32 s4, s4, 0x40080
	v_lshl_add_u64 v[188:189], v[222:223], 0, s[48:49]
	s_addc_u32 s5, s5, 0
	s_add_i32 s6, s18, s87
	global_load_lds_dwordx4 v[188:189], off
	v_lshl_add_u64 v[188:189], s[4:5], 0, v[158:159]
	s_mov_b32 m0, s6
	s_nop 0
	global_load_lds_dwordx4 v[188:189], off
	v_lshl_add_u64 v[188:189], s[4:5], 0, v[154:155]
	s_add_i32 m0, s6, 0x2000
	s_nop 0
	global_load_lds_dwordx4 v[188:189], off
	v_lshl_add_u64 v[188:189], v[238:239], 0, s[48:49]
	s_mov_b32 m0, s74
	s_nop 0
	global_load_lds_dwordx4 v[188:189], off
	v_lshl_add_u64 v[188:189], v[240:241], 0, s[48:49]
	s_mov_b32 m0, s75
	s_nop 0
	global_load_lds_dwordx4 v[188:189], off
	s_waitcnt vmcnt(8)
	s_waitcnt lgkmcnt(0)
	s_barrier
	s_setprio 1
	s_waitcnt lgkmcnt(0)
	v_mfma_f32_16x16x32_bf16 v[78:81], v[50:53], v[180:183], v[78:81]
	v_mfma_f32_16x16x32_bf16 v[74:77], v[66:69], v[180:183], v[74:77]
	s_add_i32 s16, s16, 2
	s_add_u32 s0, s0, 0x100
	s_addc_u32 s1, s1, 0
	s_add_u32 s14, s14, 0x100
	s_addc_u32 s15, s15, 0
	s_add_u32 s4, s0, 0xfffc0080
	s_addc_u32 s5, s1, -1
	s_add_i32 s17, 0, 0x10000
	s_cmp_eq_u32 s16, 12
	s_cselect_b32 s7, s9, s5
	s_cselect_b32 s6, s11, s4
	v_add_u32_e32 v0, s17, v198
	s_cselect_b32 s5, s12, s15
	s_cselect_b32 s4, s13, s14
	s_add_i32 s20, 0, 0x14000
	s_cmp_gt_u32 s16, 13
	v_mfma_f32_16x16x32_bf16 v[62:65], v[50:53], v[202:205], v[62:65]
	v_mfma_f32_16x16x32_bf16 v[58:61], v[66:69], v[202:205], v[58:61]
	v_mfma_f32_16x16x32_bf16 v[46:49], v[50:53], v[210:213], v[46:49]
	v_mfma_f32_16x16x32_bf16 v[42:45], v[66:69], v[210:213], v[42:45]
	v_mfma_f32_16x16x32_bf16 v[14:17], v[50:53], v[218:221], v[14:17]
	v_mfma_f32_16x16x32_bf16 v[10:13], v[66:69], v[218:221], v[10:13]
	v_mfma_f32_16x16x32_bf16 v[78:81], v[54:57], v[184:187], v[78:81]
	v_mfma_f32_16x16x32_bf16 v[74:77], v[70:73], v[184:187], v[74:77]
	v_mfma_f32_16x16x32_bf16 v[62:65], v[54:57], v[206:209], v[62:65]
	v_mfma_f32_16x16x32_bf16 v[58:61], v[70:73], v[206:209], v[58:61]
	v_mfma_f32_16x16x32_bf16 v[46:49], v[54:57], v[214:217], v[46:49]
	v_mfma_f32_16x16x32_bf16 v[42:45], v[70:73], v[214:217], v[42:45]
	v_mfma_f32_16x16x32_bf16 v[14:17], v[54:57], v[234:237], v[14:17]
	v_mfma_f32_16x16x32_bf16 v[10:13], v[70:73], v[234:237], v[10:13]
	s_setprio 0
	s_setprio 1
	v_mfma_f32_16x16x32_bf16 v[18:21], v[146:149], v[180:183], v[18:21]
	v_mfma_f32_16x16x32_bf16 v[70:73], v[150:153], v[184:187], v[18:21]
	v_mfma_f32_16x16x32_bf16 v[18:21], v[172:175], v[180:183], v[22:25]
	v_mfma_f32_16x16x32_bf16 v[66:69], v[176:179], v[184:187], v[18:21]
	v_mfma_f32_16x16x32_bf16 v[18:21], v[146:149], v[202:205], v[34:37]
	v_mfma_f32_16x16x32_bf16 v[54:57], v[150:153], v[206:209], v[18:21]
	v_mfma_f32_16x16x32_bf16 v[18:21], v[172:175], v[202:205], v[38:41]
	v_mfma_f32_16x16x32_bf16 v[50:53], v[176:179], v[206:209], v[18:21]
	v_mfma_f32_16x16x32_bf16 v[18:21], v[146:149], v[210:213], v[30:33]
	v_mfma_f32_16x16x32_bf16 v[30:33], v[150:153], v[214:217], v[18:21]
	v_mfma_f32_16x16x32_bf16 v[18:21], v[172:175], v[210:213], v[26:29]
	v_mfma_f32_16x16x32_bf16 v[6:9], v[146:149], v[218:221], v[6:9]
	v_mfma_f32_16x16x32_bf16 v[2:5], v[172:175], v[218:221], v[2:5]
	v_mfma_f32_16x16x32_bf16 v[26:29], v[176:179], v[214:217], v[18:21]
	v_mfma_f32_16x16x32_bf16 v[6:9], v[150:153], v[234:237], v[6:9]
	v_mfma_f32_16x16x32_bf16 v[2:5], v[176:179], v[234:237], v[2:5]
	s_setprio 0
	s_barrier
	s_cbranch_scc0 .LBB0_57
	v_readlane_b32 s0, v255, 4
	v_readlane_b32 s1, v255, 5
	s_and_b64 vcc, exec, s[0:1]
	s_cbranch_vccz .LBB0_60
	s_barrier
